# v20: v18 + grid barrier followers wait on the global generation word directly (one polling hop less per barrier)
# baseline (speedup 1.0000x reference)
.LBB0_105:
	s_or_b64 exec, exec, s[10:11]
	v_cvt_f32_u32_e32 v4, v2
	s_waitcnt vmcnt(0)
	v_readfirstlane_b32 s2, v3
	v_sub_u32_e32 v3, 0, v2
	v_rcp_iflag_f32_e32 v4, v4
	v_add_u32_e32 v5, s2, v0
	v_mul_f32_e32 v4, 0x4f7ffffe, v4
	v_cvt_u32_f32_e32 v4, v4
	v_mul_lo_u32 v0, v3, v4
	v_mul_hi_u32 v0, v4, v0
	v_add_u32_e32 v0, v4, v0
	v_mul_hi_u32 v0, v5, v0
	v_mul_lo_u32 v3, v0, v2
	v_sub_u32_e32 v3, v5, v3
	v_add_u32_e32 v4, 1, v0
	v_cmp_ge_u32_e32 vcc, v3, v2
	s_nop 1
	v_cndmask_b32_e32 v0, v0, v4, vcc
	v_sub_u32_e32 v4, v3, v2
	v_cndmask_b32_e32 v3, v3, v4, vcc
	v_add_u32_e32 v4, 1, v0
	v_cmp_ge_u32_e32 vcc, v3, v2
	v_add_u32_e32 v3, 1, v5
	s_nop 0
	v_cndmask_b32_e32 v0, v0, v4, vcc
	v_mul_lo_u32 v4, v2, v0
	v_add_u32_e32 v2, v4, v2
	v_cmp_ne_u32_e32 vcc, v3, v2
	s_and_saveexec_b64 s[8:9], vcc
	s_xor_b64 s[8:9], exec, s[8:9]
	s_cbranch_execz .LBB0_119
	s_waitcnt lgkmcnt(0)
	v_mov_b32_e32 v1, 0x9883000
	global_load_dword v1, v1, s[4:5] offset:1280 sc1
	s_add_u32 s14, s4, 0x9883500
	s_addc_u32 s15, s5, 0
	s_waitcnt vmcnt(0)
	v_cmp_eq_u32_e32 vcc, v1, v0
	s_and_saveexec_b64 s[10:11], vcc
	s_cbranch_execz .LBB0_118
	s_add_u32 s12, s4, 0x9880200
	s_addc_u32 s13, s5, 0
	s_mov_b32 s2, 1
	s_mov_b64 s[16:17], 0
	v_mov_b32_e32 v1, 0
	s_branch .LBB0_109

.LBB0_273:
	s_or_b64 exec, exec, s[12:13]
	v_cvt_f32_u32_e32 v5, v3
	s_waitcnt vmcnt(0)
	v_readfirstlane_b32 s2, v4
	v_sub_u32_e32 v4, 0, v3
	v_rcp_iflag_f32_e32 v5, v5
	v_add_u32_e32 v6, s2, v1
	v_mul_f32_e32 v5, 0x4f7ffffe, v5
	v_cvt_u32_f32_e32 v5, v5
	v_mul_lo_u32 v1, v4, v5
	v_mul_hi_u32 v1, v5, v1
	v_add_u32_e32 v1, v5, v1
	v_mul_hi_u32 v1, v6, v1
	v_mul_lo_u32 v4, v1, v3
	v_sub_u32_e32 v4, v6, v4
	v_add_u32_e32 v5, 1, v1
	v_cmp_ge_u32_e32 vcc, v4, v3
	s_nop 1
	v_cndmask_b32_e32 v1, v1, v5, vcc
	v_sub_u32_e32 v5, v4, v3
	v_cndmask_b32_e32 v4, v4, v5, vcc
	v_add_u32_e32 v5, 1, v1
	v_cmp_ge_u32_e32 vcc, v4, v3
	v_add_u32_e32 v4, 1, v6
	s_nop 0
	v_cndmask_b32_e32 v1, v1, v5, vcc
	v_mul_lo_u32 v5, v3, v1
	v_add_u32_e32 v3, v5, v3
	v_cmp_ne_u32_e32 vcc, v4, v3
	s_and_saveexec_b64 s[2:3], vcc
	s_xor_b64 s[8:9], exec, s[2:3]
	s_cbranch_execz .LBB0_287
	s_waitcnt lgkmcnt(0)
	global_load_dword v0, v233, s[4:5] offset:1280 sc1
	s_add_u32 s16, s4, 0x9883500
	s_addc_u32 s17, s5, 0
	s_waitcnt vmcnt(0)
	v_cmp_eq_u32_e32 vcc, v0, v1
	s_and_saveexec_b64 s[12:13], vcc
	s_cbranch_execz .LBB0_286
	s_add_u32 s14, s4, 0x9880200
	s_addc_u32 s15, s5, 0
	s_mov_b32 s2, 1
	s_mov_b64 s[18:19], 0
	s_branch .LBB0_277

.LBB0_347:
	s_or_b64 exec, exec, s[10:11]
	v_cvt_f32_u32_e32 v5, v3
	s_waitcnt vmcnt(0)
	v_readfirstlane_b32 s2, v4
	v_sub_u32_e32 v4, 0, v3
	v_rcp_iflag_f32_e32 v5, v5
	v_add_u32_e32 v6, s2, v1
	v_mul_f32_e32 v5, 0x4f7ffffe, v5
	v_cvt_u32_f32_e32 v5, v5
	v_mul_lo_u32 v1, v4, v5
	v_mul_hi_u32 v1, v5, v1
	v_add_u32_e32 v1, v5, v1
	v_mul_hi_u32 v1, v6, v1
	v_mul_lo_u32 v4, v1, v3
	v_sub_u32_e32 v4, v6, v4
	v_add_u32_e32 v5, 1, v1
	v_cmp_ge_u32_e32 vcc, v4, v3
	s_nop 1
	v_cndmask_b32_e32 v1, v1, v5, vcc
	v_sub_u32_e32 v5, v4, v3
	v_cndmask_b32_e32 v4, v4, v5, vcc
	v_add_u32_e32 v5, 1, v1
	v_cmp_ge_u32_e32 vcc, v4, v3
	v_add_u32_e32 v4, 1, v6
	s_nop 0
	v_cndmask_b32_e32 v1, v1, v5, vcc
	v_mul_lo_u32 v5, v3, v1
	v_add_u32_e32 v3, v5, v3
	v_cmp_ne_u32_e32 vcc, v4, v3
	s_and_saveexec_b64 s[2:3], vcc
	s_xor_b64 s[8:9], exec, s[2:3]
	s_cbranch_execz .LBB0_361
	s_waitcnt lgkmcnt(0)
	global_load_dword v0, v233, s[4:5] offset:1280 sc1
	s_add_u32 s14, s4, 0x9883500
	s_addc_u32 s15, s5, 0
	s_waitcnt vmcnt(0)
	v_cmp_eq_u32_e32 vcc, v0, v1
	s_and_saveexec_b64 s[10:11], vcc
	s_cbranch_execz .LBB0_360
	s_add_u32 s12, s4, 0x9880200
	s_addc_u32 s13, s5, 0
	s_mov_b32 s2, 1
	s_mov_b64 s[16:17], 0
	s_branch .LBB0_351
